# row phases P1a/P3b/P6b: modulation-vector prologue loads issued in one batch per iteration (one wait instead of 3-4)
# speedup vs baseline: 1.0074x; 1.0020x over previous
; __device__ __forceinline__ float mod_val(const float* modp, const float* adab, int l, int b, int j) {
;     float s = adab[l * 3072 + j];
; #pragma unroll
;     for (int kc = 0; kc < KS; ++kc) s += modp[((size_t)(kc * 2 + l) * 8 + b) * 3072 + j];
;     return s;
; }
; __device__ __forceinline__ void p1a_rows(const Args& A, char* lds, int G) {
;     ...
;         for (int col = tid; col < 1024; col += NTHR) { mv[col] = A.in[I_PREG][col] * (1.f + mod_val(modp, A.in[I_ADAB], 0, b, 1024 + col)); mv[1024 + col] = mod_val(modp, A.in[I_ADAB], 0, b, col); }
.LBB0_385:
	v_lshl_add_u64 v[8:9], v[70:71], 0, s[10:11]
	v_lshl_add_u64 v[10:11], v[0:1], 0, s[10:11]
	flat_load_dword v24, v[8:9]
	flat_load_dword v25, v[10:11]
	v_add_co_u32_e32 v8, vcc, 0x30000, v10
	v_lshl_add_u64 v[6:7], v[76:77], 0, s[10:11]
	s_nop 0
	v_addc_co_u32_e32 v9, vcc, 0, v11, vcc
	v_add_co_u32_e32 v12, vcc, 0x60000, v10
	flat_load_dword v26, v[8:9]
	s_nop 0
	v_addc_co_u32_e32 v13, vcc, 0, v11, vcc
	v_add_co_u32_e32 v8, vcc, 0x90000, v10
	v_add_u32_e32 v5, 0x200, v5
	s_nop 0
	v_addc_co_u32_e32 v9, vcc, 0, v11, vcc
	v_add_co_u32_e32 v14, vcc, 0xc0000, v10
	flat_load_dword v27, v[12:13]
	flat_load_dword v28, v[8:9]
	v_addc_co_u32_e32 v15, vcc, 0, v11, vcc
	v_add_co_u32_e32 v8, vcc, 0xf0000, v10
	s_nop 0
	s_nop 0
	v_addc_co_u32_e32 v9, vcc, 0, v11, vcc
	v_add_co_u32_e32 v12, vcc, 0x120000, v10
	flat_load_dword v29, v[14:15]
	flat_load_dword v30, v[8:9]
	v_addc_co_u32_e32 v13, vcc, 0, v11, vcc
	v_add_co_u32_e32 v8, vcc, 0x150000, v10
	s_nop 0
	s_nop 0
	v_addc_co_u32_e32 v9, vcc, 0, v11, vcc
	flat_load_dword v31, v[12:13]
	flat_load_dword v32, v[8:9]
	flat_load_dword v33, v[6:7]
	v_lshl_add_u64 v[8:9], v[2:3], 0, s[10:11]
	v_add_co_u32_e32 v10, vcc, s1, v8
	s_nop 0
	s_nop 0
	v_addc_co_u32_e32 v11, vcc, 0, v9, vcc
	v_add_co_u32_e32 v12, vcc, s3, v8
	s_nop 0
	s_nop 0
	v_addc_co_u32_e32 v13, vcc, 0, v9, vcc
	v_add_co_u32_e32 v14, vcc, s12, v8
	v_lshl_add_u64 v[6:7], v[74:75], 0, s[10:11]
	s_nop 0
	v_addc_co_u32_e32 v15, vcc, 0, v9, vcc
	v_add_co_u32_e32 v16, vcc, s13, v8
	s_add_u32 s10, s10, 0x800
	s_nop 0
	v_addc_co_u32_e32 v17, vcc, 0, v9, vcc
	v_add_co_u32_e32 v18, vcc, s14, v8
	s_addc_u32 s11, s11, 0
	s_nop 0
	v_addc_co_u32_e32 v19, vcc, 0, v9, vcc
	v_add_co_u32_e32 v20, vcc, s15, v8
	s_nop 0
	s_nop 0
	s_nop 0
	v_addc_co_u32_e32 v21, vcc, 0, v9, vcc
	v_add_co_u32_e32 v22, vcc, s16, v8
	s_nop 0
	s_nop 0
	s_nop 0
	s_nop 0
	s_nop 0
	v_addc_co_u32_e32 v23, vcc, 0, v9, vcc
	flat_load_dword v34, v[6:7]
	flat_load_dword v35, v[8:9]
	flat_load_dword v36, v[10:11]
	flat_load_dword v37, v[12:13]
	flat_load_dword v38, v[14:15]
	flat_load_dword v39, v[16:17]
	flat_load_dword v40, v[18:19]
	flat_load_dword v41, v[20:21]
	flat_load_dword v42, v[22:23]
	v_cmp_lt_i32_e32 vcc, s17, v5
	s_or_b64 s[8:9], vcc, s[8:9]
	s_waitcnt vmcnt(0) lgkmcnt(0)
	v_add_f32_e32 v24, v24, v25
	v_add_f32_e32 v24, v24, v26
	v_add_f32_e32 v24, v24, v27
	v_add_f32_e32 v24, v24, v28
	v_add_f32_e32 v24, v24, v29
	v_add_f32_e32 v24, v24, v30
	v_add_f32_e32 v24, v24, v31
	v_add_f32_e32 v24, v24, v32
	v_add_f32_e32 v24, 1.0, v24
	v_mul_f32_e32 v24, v33, v24
	ds_write_b32 v4, v24
	v_add_f32_e32 v6, v34, v35
	v_add_f32_e32 v6, v6, v36
	v_add_f32_e32 v6, v6, v37
	v_add_f32_e32 v6, v6, v38
	v_add_f32_e32 v6, v6, v39
	v_add_f32_e32 v6, v6, v40
	v_add_f32_e32 v6, v6, v41
	v_add_f32_e32 v6, v6, v42
	ds_write_b32 v4, v6 offset:4096
	v_add_u32_e32 v4, 0x800, v4
	s_andn2_b64 exec, exec, s[8:9]
	s_cbranch_execnz .LBB0_385

; __device__ __forceinline__ float mod_val(const float* modp, const float* adab, int l, int b, int j) {
;     float s = adab[l * 3072 + j];
; #pragma unroll
;     for (int kc = 0; kc < KS; ++kc) s += modp[((size_t)(kc * 2 + l) * 8 + b) * 3072 + j];
;     return s;
; }
; __device__ __forceinline__ void p3b_rows(const Args& A, char* lds, int G) {
;     ...
;         for (int col = tid; col < 1024; col += NTHR) { mv[col] = A.in[I_POSTG][col] * mod_val(modp, A.in[I_ADAB], 0, b, 2048 + col);
;             mv[1024 + col] = A.in[I_PREG][1024 + col] * (1.f + mod_val(modp, A.in[I_ADAB], 1, b, 1024 + col)); mv[2048 + col] = mod_val(modp, A.in[I_ADAB], 1, b, col); }
.LBB0_1173:
	v_lshl_add_u64 v[10:11], v[94:95], 0, s[16:17]
	v_lshl_add_u64 v[12:13], v[2:3], 0, s[16:17]
	flat_load_dword v30, v[10:11]
	flat_load_dword v31, v[12:13]
	v_add_co_u32_e32 v10, vcc, 0x30000, v12
	v_lshl_add_u64 v[8:9], v[100:101], 0, s[16:17]
	s_nop 0
	v_addc_co_u32_e32 v11, vcc, 0, v13, vcc
	v_add_co_u32_e32 v14, vcc, 0x60000, v12
	flat_load_dword v32, v[10:11]
	s_nop 0
	v_addc_co_u32_e32 v15, vcc, 0, v13, vcc
	v_add_co_u32_e32 v10, vcc, 0x90000, v12
	v_add_u32_e32 v7, 0x200, v7
	s_nop 0
	v_addc_co_u32_e32 v11, vcc, 0, v13, vcc
	v_add_co_u32_e32 v16, vcc, 0xc0000, v12
	flat_load_dword v33, v[14:15]
	flat_load_dword v34, v[10:11]
	v_addc_co_u32_e32 v17, vcc, 0, v13, vcc
	v_add_co_u32_e32 v10, vcc, 0xf0000, v12
	s_nop 0
	s_nop 0
	v_addc_co_u32_e32 v11, vcc, 0, v13, vcc
	v_add_co_u32_e32 v14, vcc, 0x120000, v12
	flat_load_dword v35, v[16:17]
	flat_load_dword v36, v[10:11]
	v_addc_co_u32_e32 v15, vcc, 0, v13, vcc
	v_add_co_u32_e32 v10, vcc, 0x150000, v12
	s_nop 0
	s_nop 0
	v_addc_co_u32_e32 v11, vcc, 0, v13, vcc
	flat_load_dword v37, v[14:15]
	flat_load_dword v38, v[10:11]
	flat_load_dword v39, v[8:9]
	v_lshl_add_u64 v[10:11], v[98:99], 0, s[16:17]
	v_add_co_u32_e32 v14, vcc, 0x4000, v10
	v_lshl_add_u64 v[12:13], v[0:1], 0, s[16:17]
	s_nop 0
	v_addc_co_u32_e32 v15, vcc, 0, v11, vcc
	v_add_co_u32_e32 v16, vcc, 0x18000, v12
	s_nop 0
	s_nop 0
	v_addc_co_u32_e32 v17, vcc, 0, v13, vcc
	v_add_co_u32_e32 v18, vcc, 0x48000, v12
	s_nop 0
	s_nop 0
	v_addc_co_u32_e32 v19, vcc, 0, v13, vcc
	v_add_co_u32_e32 v20, vcc, 0x78000, v12
	v_lshl_add_u64 v[8:9], v[90:91], 0, s[16:17]
	s_nop 0
	v_addc_co_u32_e32 v21, vcc, 0, v13, vcc
	v_add_co_u32_e32 v22, vcc, 0xa8000, v12
	s_nop 0
	s_nop 0
	v_addc_co_u32_e32 v23, vcc, 0, v13, vcc
	v_add_co_u32_e32 v24, vcc, 0xd8000, v12
	s_nop 0
	s_nop 0
	v_addc_co_u32_e32 v25, vcc, 0, v13, vcc
	v_add_co_u32_e32 v26, vcc, 0x108000, v12
	s_nop 0
	s_nop 0
	v_addc_co_u32_e32 v27, vcc, 0, v13, vcc
	v_add_co_u32_e32 v28, vcc, 0x138000, v12
	s_nop 0
	s_nop 0
	v_addc_co_u32_e32 v29, vcc, 0, v13, vcc
	s_nop 0
	v_add_co_u32_e32 v12, vcc, 0x168000, v12
	s_nop 0
	s_nop 0
	v_addc_co_u32_e32 v13, vcc, 0, v13, vcc
	flat_load_dword v150, v[14:15]
	flat_load_dword v151, v[16:17]
	flat_load_dword v152, v[18:19]
	flat_load_dword v153, v[20:21]
	flat_load_dword v154, v[22:23]
	flat_load_dword v155, v[24:25]
	flat_load_dword v156, v[26:27]
	flat_load_dword v157, v[28:29]
	flat_load_dword v158, v[12:13]
	flat_load_dword v159, v[8:9]
	v_add_co_u32_e32 v10, vcc, s1, v10
	v_lshl_add_u64 v[8:9], v[4:5], 0, s[16:17]
	s_nop 0
	v_addc_co_u32_e32 v11, vcc, 0, v11, vcc
	v_add_co_u32_e32 v12, vcc, s4, v8
	s_add_u32 s16, s16, 0x800
	s_nop 0
	v_addc_co_u32_e32 v13, vcc, 0, v9, vcc
	v_add_co_u32_e32 v14, vcc, s5, v8
	s_addc_u32 s17, s17, 0
	s_nop 0
	v_addc_co_u32_e32 v15, vcc, 0, v9, vcc
	v_add_co_u32_e32 v16, vcc, s18, v8
	s_nop 0
	s_nop 0
	v_addc_co_u32_e32 v17, vcc, 0, v9, vcc
	s_nop 0
	v_add_co_u32_e32 v18, vcc, s19, v8
	s_nop 0
	s_nop 0
	v_addc_co_u32_e32 v19, vcc, 0, v9, vcc
	s_nop 0
	v_add_co_u32_e32 v20, vcc, s20, v8
	s_nop 0
	s_nop 0
	v_addc_co_u32_e32 v21, vcc, 0, v9, vcc
	s_nop 0
	v_add_co_u32_e32 v22, vcc, s21, v8
	s_nop 0
	s_nop 0
	v_addc_co_u32_e32 v23, vcc, 0, v9, vcc
	s_nop 0
	v_add_co_u32_e32 v24, vcc, s22, v8
	s_nop 0
	s_nop 0
	v_addc_co_u32_e32 v25, vcc, 0, v9, vcc
	s_nop 0
	v_add_co_u32_e32 v8, vcc, s23, v8
	s_nop 0
	s_nop 0
	v_addc_co_u32_e32 v9, vcc, 0, v9, vcc
	flat_load_dword v160, v[10:11]
	flat_load_dword v161, v[12:13]
	flat_load_dword v162, v[14:15]
	flat_load_dword v163, v[16:17]
	flat_load_dword v164, v[18:19]
	flat_load_dword v165, v[20:21]
	flat_load_dword v166, v[22:23]
	flat_load_dword v167, v[24:25]
	flat_load_dword v168, v[8:9]
	v_cmp_lt_i32_e32 vcc, s24, v7
	s_or_b64 s[14:15], vcc, s[14:15]
	s_waitcnt vmcnt(0) lgkmcnt(0)
	v_add_f32_e32 v30, v30, v31
	v_add_f32_e32 v30, v30, v32
	v_add_f32_e32 v30, v30, v33
	v_add_f32_e32 v30, v30, v34
	v_add_f32_e32 v30, v30, v35
	v_add_f32_e32 v30, v30, v36
	v_add_f32_e32 v30, v30, v37
	v_add_f32_e32 v30, v30, v38
	v_mul_f32_e32 v30, v39, v30
	ds_write_b32 v6, v30
	v_add_f32_e32 v26, v150, v151
	v_add_f32_e32 v26, v26, v152
	v_add_f32_e32 v26, v26, v153
	v_add_f32_e32 v26, v26, v154
	v_add_f32_e32 v26, v26, v155
	v_add_f32_e32 v26, v26, v156
	v_add_f32_e32 v26, v26, v157
	v_add_f32_e32 v26, v26, v158
	v_add_f32_e32 v26, 1.0, v26
	v_mul_f32_e32 v26, v159, v26
	ds_write_b32 v6, v26 offset:4096
	v_add_f32_e32 v8, v160, v161
	v_add_f32_e32 v8, v8, v162
	v_add_f32_e32 v8, v8, v163
	v_add_f32_e32 v8, v8, v164
	v_add_f32_e32 v8, v8, v165
	v_add_f32_e32 v8, v8, v166
	v_add_f32_e32 v8, v8, v167
	v_add_f32_e32 v8, v8, v168
	ds_write_b32 v6, v8 offset:8192
	v_add_u32_e32 v6, 0x800, v6
	s_andn2_b64 exec, exec, s[14:15]
	s_cbranch_execnz .LBB0_1173

; __device__ __forceinline__ float mod_val(const float* modp, const float* adab, int l, int b, int j) {
;     float s = adab[l * 3072 + j];
; #pragma unroll
;     for (int kc = 0; kc < KS; ++kc) s += modp[((size_t)(kc * 2 + l) * 8 + b) * 3072 + j];
;     return s;
; }
; __device__ __forceinline__ void p6b_rows(const Args& A, char* lds, int G) {
;     ...
;         for (int col = tid; col < 1024; col += NTHR) { mv[col] = A.in[I_POSTG][col] * mod_val(modp, A.in[I_ADAB], 0, b, 2048 + col); mv[1024 + col] = A.in[I_POSTG][1024 + col] * mod_val(modp, A.in[I_ADAB], 1, b, 2048 + col); }
.LBB0_1650:
	v_lshl_add_u64 v[6:7], v[74:75], 0, s[14:15]
	v_lshl_add_u64 v[8:9], v[0:1], 0, s[14:15]
	flat_load_dword v24, v[6:7]
	flat_load_dword v25, v[8:9]
	v_add_co_u32_e32 v6, vcc, 0x30000, v8
	v_lshl_add_u64 v[4:5], v[78:79], 0, s[14:15]
	s_nop 0
	v_addc_co_u32_e32 v7, vcc, 0, v9, vcc
	v_add_co_u32_e32 v10, vcc, 0x60000, v8
	flat_load_dword v26, v[6:7]
	s_nop 0
	v_addc_co_u32_e32 v11, vcc, 0, v9, vcc
	v_add_co_u32_e32 v6, vcc, 0x90000, v8
	v_add_u32_e32 v3, 0x200, v3
	s_nop 0
	v_addc_co_u32_e32 v7, vcc, 0, v9, vcc
	v_add_co_u32_e32 v12, vcc, 0xc0000, v8
	flat_load_dword v27, v[10:11]
	flat_load_dword v28, v[6:7]
	v_addc_co_u32_e32 v13, vcc, 0, v9, vcc
	v_add_co_u32_e32 v6, vcc, 0xf0000, v8
	s_nop 0
	s_nop 0
	v_addc_co_u32_e32 v7, vcc, 0, v9, vcc
	v_add_co_u32_e32 v10, vcc, 0x120000, v8
	flat_load_dword v29, v[12:13]
	flat_load_dword v30, v[6:7]
	v_addc_co_u32_e32 v11, vcc, 0, v9, vcc
	v_add_co_u32_e32 v6, vcc, 0x150000, v8
	s_nop 0
	s_nop 0
	v_addc_co_u32_e32 v7, vcc, 0, v9, vcc
	flat_load_dword v31, v[10:11]
	flat_load_dword v32, v[6:7]
	flat_load_dword v33, v[4:5]
	v_add_co_u32_e32 v4, vcc, 0x1000, v4
	v_lshl_add_u64 v[6:7], v[76:77], 0, s[14:15]
	s_nop 0
	v_addc_co_u32_e32 v5, vcc, 0, v5, vcc
	v_add_co_u32_e32 v10, vcc, 0x18000, v8
	s_nop 0
	s_nop 0
	v_addc_co_u32_e32 v11, vcc, 0, v9, vcc
	v_add_co_u32_e32 v12, vcc, 0x48000, v8
	s_nop 0
	s_nop 0
	v_addc_co_u32_e32 v13, vcc, 0, v9, vcc
	v_add_co_u32_e32 v14, vcc, 0x78000, v8
	s_add_u32 s14, s14, 0x800
	s_nop 0
	v_addc_co_u32_e32 v15, vcc, 0, v9, vcc
	v_add_co_u32_e32 v16, vcc, 0xa8000, v8
	s_addc_u32 s15, s15, 0
	s_nop 0
	v_addc_co_u32_e32 v17, vcc, 0, v9, vcc
	v_add_co_u32_e32 v18, vcc, 0xd8000, v8
	s_nop 0
	s_nop 0
	v_addc_co_u32_e32 v19, vcc, 0, v9, vcc
	v_add_co_u32_e32 v20, vcc, 0x108000, v8
	s_nop 0
	s_nop 0
	v_addc_co_u32_e32 v21, vcc, 0, v9, vcc
	s_nop 0
	v_add_co_u32_e32 v22, vcc, 0x138000, v8
	s_nop 0
	s_nop 0
	v_addc_co_u32_e32 v23, vcc, 0, v9, vcc
	s_nop 0
	v_add_co_u32_e32 v8, vcc, 0x168000, v8
	s_nop 0
	s_nop 0
	v_addc_co_u32_e32 v9, vcc, 0, v9, vcc
	flat_load_dword v160, v[6:7]
	flat_load_dword v161, v[10:11]
	flat_load_dword v162, v[12:13]
	flat_load_dword v163, v[14:15]
	flat_load_dword v164, v[16:17]
	flat_load_dword v165, v[18:19]
	flat_load_dword v166, v[20:21]
	flat_load_dword v167, v[22:23]
	flat_load_dword v168, v[8:9]
	flat_load_dword v169, v[4:5]
	v_cmp_lt_i32_e32 vcc, s11, v3
	s_or_b64 s[12:13], vcc, s[12:13]
	s_waitcnt vmcnt(0) lgkmcnt(0)
	v_add_f32_e32 v24, v24, v25
	v_add_f32_e32 v24, v24, v26
	v_add_f32_e32 v24, v24, v27
	v_add_f32_e32 v24, v24, v28
	v_add_f32_e32 v24, v24, v29
	v_add_f32_e32 v24, v24, v30
	v_add_f32_e32 v24, v24, v31
	v_add_f32_e32 v24, v24, v32
	v_mul_f32_e32 v24, v33, v24
	ds_write_b32 v2, v24
	v_add_f32_e32 v4, v160, v161
	v_add_f32_e32 v4, v4, v162
	v_add_f32_e32 v4, v4, v163
	v_add_f32_e32 v4, v4, v164
	v_add_f32_e32 v4, v4, v165
	v_add_f32_e32 v4, v4, v166
	v_add_f32_e32 v4, v4, v167
	v_add_f32_e32 v4, v4, v168
	v_mul_f32_e32 v4, v169, v4
	ds_write_b32 v2, v4 offset:4096
	v_add_u32_e32 v2, 0x800, v2
	s_andn2_b64 exec, exec, s[12:13]
	s_cbranch_execnz .LBB0_1650
